# loop-edge edit: GEMM K-loop head scalar pointer/counter updates moved behind the first four LDS fragment reads
# speedup vs baseline: 1.0027x; 1.0027x over previous
; #define PG8_STAGE(bufoff, gbase, voff) do { _Pragma("unroll") for (int _i = 0; _i < 2; ++_i) \
;     __builtin_amdgcn_global_load_lds((const unsigned*)((const char*)(gbase) + (voff)[_i]), (LAS unsigned*)(lds + (bufoff) + ldsw + _i * 8192), 16, 0, 0); } while (0)
; #define PG8_LDA(dst, b, h) do { _Pragma("unroll") for (int m = 0; m < 4; ++m) _Pragma("unroll") for (int k = 0; k < 2; ++k) dst[m][k] = *(const LAS bf16x8*)(lds + PG8_SA(b, h) + aoff + m * 2048 + k * 1024); } while (0)
; #define PG8_LDB(dst, b, h) do { _Pragma("unroll") for (int n = 0; n < 2; ++n) _Pragma("unroll") for (int k = 0; k < 2; ++k) dst[n][k] = *(const LAS bf16x8*)(lds + PG8_SB(b, h) + boff + n * 2048 + k * 1024); } while (0)
; #define PG8_MMA(ai, bj, At, Bt) do { __builtin_amdgcn_s_setprio(1); _Pragma("unroll") for (int m = 0; m < 4; ++m) _Pragma("unroll") for (int n = 0; n < 2; ++n) _Pragma("unroll") for (int k = 0; k < 2; ++k) \
;     acc[ai][bj][m][n] = __builtin_amdgcn_mfma_f32_16x16x32_bf16(Bt[n][k], At[m][k], acc[ai][bj][m][n], 0, 0, 0); __builtin_amdgcn_s_setprio(0); } while (0)
; #define PG8_WAIT_L(n) asm volatile("s_waitcnt lgkmcnt(" #n ")" ::: "memory")
; #define PG8_BAR __builtin_amdgcn_s_barrier()
; #define PG8_SCHED __builtin_amdgcn_sched_barrier(0)
; __device__ __forceinline__ void gemm_phase(LAS unsigned char* lds, const Gemm g, const StaticOrder& S, const Epi& E, const int tid) {
;     ...
;     for (int t = 0; t < nt; t += 2) {
;       const bool last = (t == nt - 2);
;       const char* a1 = cA + (size_t)(t + 1) * kstep;
;       const char* a2 = last ? nA : cA + (size_t)(t + 2) * kstep; const char* b2 = last ? nB : cB + (size_t)(t + 2) * kstep;
;       const char* a3 = a2 + kstep; const char* b3 = b2 + kstep;
;       PG8_LDB(B0, 0, 0); PG8_SCHED; PG8_LDA(At, 0, 0); PG8_STAGE(PG8_SA(1, 1), a1 + hstep, voffA);
;       PG8_WAIT_L(8); PG8_BAR; PG8_WAIT_L(0); PG8_MMA(0, 0, At, B0); PG8_BAR; PG8_SCHED;
;       PG8_LDB(B1, 0, 1); PG8_STAGE(PG8_SB(0, 0), b2, voffB);
;       PG8_BAR; PG8_WAIT_L(0); PG8_MMA(0, 1, At, B1); PG8_BAR;
;       PG8_LDA(At, 0, 1); PG8_STAGE(PG8_SA(0, 0), a2, voffA);
;       PG8_BAR; PG8_WAIT_L(0); PG8_MMA(1, 0, At, B0); PG8_BAR; PG8_SCHED;
.LBB0_299:
	s_add_i32 s71, 0, 0x10000
	v_add_u32_e32 v136, s71, v205
	ds_read_b128 v[128:131], v136
	ds_read_b128 v[132:135], v136 offset:1024
	ds_read_b128 v[158:161], v136 offset:2048
	ds_read_b128 v[162:165], v136 offset:3072
	s_add_i32 s70, s10, 2
	s_add_u32 s68, s8, 0x80
	s_addc_u32 s11, s9, 0
	s_cmp_eq_u32 s88, s10
	s_cselect_b32 s10, s56, s68
	s_cselect_b32 s11, s57, s11
	s_cselect_b32 s69, s67, vcc_hi
	s_cselect_b32 s68, s66, vcc_lo
	v_lshl_add_u64 v[136:137], s[8:9], 0, v[156:157]
	s_add_i32 m0, s75, 0xc000
	ds_read_b128 v[166:169], v208
	ds_read_b128 v[170:173], v208 offset:1024
	ds_read_b128 v[174:177], v208 offset:2048
	ds_read_b128 v[178:181], v208 offset:3072
	ds_read_b128 v[182:185], v208 offset:4096
	ds_read_b128 v[186:189], v208 offset:5120
	ds_read_b128 v[190:193], v208 offset:6144
	ds_read_b128 v[244:247], v208 offset:7168
	global_load_lds_dwordx4 v[136:137], off
	v_lshl_add_u64 v[136:137], s[8:9], 0, v[154:155]
	s_add_i32 m0, s75, 0xe000
	s_nop 0
	global_load_lds_dwordx4 v[136:137], off
	s_waitcnt lgkmcnt(8)
	s_barrier
	s_waitcnt lgkmcnt(0)
	s_setprio 1
	s_waitcnt lgkmcnt(0)
	v_mfma_f32_16x16x32_bf16 v[124:127], v[128:131], v[166:169], v[124:127]
	v_mfma_f32_16x16x32_bf16 v[120:123], v[158:161], v[166:169], v[120:123]
	v_mfma_f32_16x16x32_bf16 v[116:119], v[128:131], v[174:177], v[116:119]
	v_mfma_f32_16x16x32_bf16 v[112:115], v[158:161], v[174:177], v[112:115]
	v_mfma_f32_16x16x32_bf16 v[108:111], v[128:131], v[182:185], v[108:111]
	v_mfma_f32_16x16x32_bf16 v[104:107], v[158:161], v[182:185], v[104:107]
	v_mfma_f32_16x16x32_bf16 v[100:103], v[128:131], v[190:193], v[100:103]
	v_mfma_f32_16x16x32_bf16 v[96:99], v[158:161], v[190:193], v[96:99]
	v_mfma_f32_16x16x32_bf16 v[124:127], v[132:135], v[170:173], v[124:127]
	v_mfma_f32_16x16x32_bf16 v[120:123], v[162:165], v[170:173], v[120:123]
	v_mfma_f32_16x16x32_bf16 v[116:119], v[132:135], v[178:181], v[116:119]
	v_mfma_f32_16x16x32_bf16 v[112:115], v[162:165], v[178:181], v[112:115]
	v_mfma_f32_16x16x32_bf16 v[108:111], v[132:135], v[186:189], v[108:111]
	v_mfma_f32_16x16x32_bf16 v[104:107], v[162:165], v[186:189], v[104:107]
	v_mfma_f32_16x16x32_bf16 v[100:103], v[132:135], v[244:247], v[100:103]
	v_mfma_f32_16x16x32_bf16 v[96:99], v[162:165], v[244:247], v[96:99]
	s_setprio 0
	s_barrier
	s_add_i32 s1, 0, 0x14000
	v_add_u32_e32 v136, s1, v205
	s_add_i32 s71, s71, s74
	ds_read_b128 v[248:251], v136
	ds_read_b128 v[198:201], v136 offset:1024
	ds_read_b128 v[210:213], v136 offset:2048
	ds_read_b128 v[194:197], v136 offset:3072
	v_lshl_add_u64 v[136:137], s[68:69], 0, v[138:139]
	s_mov_b32 m0, s71
	v_lshl_add_u64 v[220:221], s[68:69], 0, v[152:153]
	global_load_lds_dwordx4 v[136:137], off
	s_add_i32 m0, s71, 0x2000
	s_nop 0
	global_load_lds_dwordx4 v[220:221], off
	s_barrier
	s_waitcnt lgkmcnt(0)
	s_setprio 1
	s_waitcnt lgkmcnt(0)
	v_mfma_f32_16x16x32_bf16 v[60:63], v[248:251], v[166:169], v[60:63]
	v_mfma_f32_16x16x32_bf16 v[56:59], v[210:213], v[166:169], v[56:59]
	v_mfma_f32_16x16x32_bf16 v[52:55], v[248:251], v[174:177], v[52:55]
	v_mfma_f32_16x16x32_bf16 v[48:51], v[210:213], v[174:177], v[48:51]
	v_mfma_f32_16x16x32_bf16 v[44:47], v[248:251], v[182:185], v[44:47]
	v_mfma_f32_16x16x32_bf16 v[40:43], v[210:213], v[182:185], v[40:43]
	v_mfma_f32_16x16x32_bf16 v[36:39], v[248:251], v[190:193], v[36:39]
	v_mfma_f32_16x16x32_bf16 v[32:35], v[210:213], v[190:193], v[32:35]
	v_mfma_f32_16x16x32_bf16 v[60:63], v[198:201], v[170:173], v[60:63]
	v_mfma_f32_16x16x32_bf16 v[56:59], v[194:197], v[170:173], v[56:59]
	v_mfma_f32_16x16x32_bf16 v[52:55], v[198:201], v[178:181], v[52:55]
	v_mfma_f32_16x16x32_bf16 v[48:51], v[194:197], v[178:181], v[48:51]
	v_mfma_f32_16x16x32_bf16 v[44:47], v[198:201], v[186:189], v[44:47]
	v_mfma_f32_16x16x32_bf16 v[40:43], v[194:197], v[186:189], v[40:43]
	v_mfma_f32_16x16x32_bf16 v[36:39], v[198:201], v[244:247], v[36:39]
	v_mfma_f32_16x16x32_bf16 v[32:35], v[194:197], v[244:247], v[32:35]
	s_setprio 0
	s_mov_b32 m0, s75
	v_lshl_add_u64 v[214:215], s[10:11], 0, v[148:149]
	s_barrier
	ds_read_b128 v[166:169], v208 offset:16384
	ds_read_b128 v[170:173], v208 offset:17408
	ds_read_b128 v[174:177], v208 offset:18432
	ds_read_b128 v[178:181], v208 offset:19456
	ds_read_b128 v[182:185], v208 offset:20480
	ds_read_b128 v[186:189], v208 offset:21504
	ds_read_b128 v[190:193], v208 offset:22528
	ds_read_b128 v[244:247], v208 offset:23552
	global_load_lds_dwordx4 v[214:215], off
	v_lshl_add_u64 v[202:203], s[10:11], 0, v[150:151]
	s_mov_b32 m0, s82
	s_nop 0
	global_load_lds_dwordx4 v[202:203], off
	s_barrier
	s_waitcnt lgkmcnt(0)
	s_setprio 1
	s_waitcnt lgkmcnt(0)
	v_mfma_f32_16x16x32_bf16 v[92:95], v[128:131], v[166:169], v[92:95]
	v_mfma_f32_16x16x32_bf16 v[88:91], v[158:161], v[166:169], v[88:91]
	v_mfma_f32_16x16x32_bf16 v[84:87], v[128:131], v[174:177], v[84:87]
	v_mfma_f32_16x16x32_bf16 v[80:83], v[158:161], v[174:177], v[80:83]
	v_mfma_f32_16x16x32_bf16 v[76:79], v[128:131], v[182:185], v[76:79]
	v_mfma_f32_16x16x32_bf16 v[72:75], v[158:161], v[182:185], v[72:75]
	v_mfma_f32_16x16x32_bf16 v[68:71], v[128:131], v[190:193], v[68:71]
	v_mfma_f32_16x16x32_bf16 v[64:67], v[158:161], v[190:193], v[64:67]
	v_mfma_f32_16x16x32_bf16 v[92:95], v[132:135], v[170:173], v[92:95]
	v_mfma_f32_16x16x32_bf16 v[88:91], v[162:165], v[170:173], v[88:91]
	v_mfma_f32_16x16x32_bf16 v[84:87], v[132:135], v[178:181], v[84:87]
	v_mfma_f32_16x16x32_bf16 v[80:83], v[162:165], v[178:181], v[80:83]
	v_mfma_f32_16x16x32_bf16 v[76:79], v[132:135], v[186:189], v[76:79]
	v_mfma_f32_16x16x32_bf16 v[72:75], v[162:165], v[186:189], v[72:75]
	v_mfma_f32_16x16x32_bf16 v[68:71], v[132:135], v[244:247], v[68:71]
	v_mfma_f32_16x16x32_bf16 v[64:67], v[162:165], v[244:247], v[64:67]
	s_setprio 0
	s_barrier
; #define PG8_STAGE(bufoff, gbase, voff) do { _Pragma("unroll") for (int _i = 0; _i < 2; ++_i) \
;     __builtin_amdgcn_global_load_lds((const unsigned*)((const char*)(gbase) + (voff)[_i]), (LAS unsigned*)(lds + (bufoff) + ldsw + _i * 8192), 16, 0, 0); } while (0)
; #define PG8_LDA(dst, b, h) do { _Pragma("unroll") for (int m = 0; m < 4; ++m) _Pragma("unroll") for (int k = 0; k < 2; ++k) dst[m][k] = *(const LAS bf16x8*)(lds + PG8_SA(b, h) + aoff + m * 2048 + k * 1024); } while (0)
; #define PG8_LDB(dst, b, h) do { _Pragma("unroll") for (int n = 0; n < 2; ++n) _Pragma("unroll") for (int k = 0; k < 2; ++k) dst[n][k] = *(const LAS bf16x8*)(lds + PG8_SB(b, h) + boff + n * 2048 + k * 1024); } while (0)
; #define PG8_MMA(ai, bj, At, Bt) do { __builtin_amdgcn_s_setprio(1); _Pragma("unroll") for (int m = 0; m < 4; ++m) _Pragma("unroll") for (int n = 0; n < 2; ++n) _Pragma("unroll") for (int k = 0; k < 2; ++k) \
;     acc[ai][bj][m][n] = __builtin_amdgcn_mfma_f32_16x16x32_bf16(Bt[n][k], At[m][k], acc[ai][bj][m][n], 0, 0, 0); __builtin_amdgcn_s_setprio(0); } while (0)
; #define PG8_WAIT_V(n) asm volatile("s_waitcnt vmcnt(" #n ")" ::: "memory")
; #define PG8_WAIT_L(n) asm volatile("s_waitcnt lgkmcnt(" #n ")" ::: "memory")
; #define PG8_BAR __builtin_amdgcn_s_barrier()
; #define PG8_SCHED __builtin_amdgcn_sched_barrier(0)
; __device__ __forceinline__ void gemm_phase(LAS unsigned char* lds, const Gemm g, const StaticOrder& S, const Epi& E, const int tid) {
;     ...
;       PG8_STAGE(PG8_SB(0, 1), b2 + hstep, voffB);
;       PG8_WAIT_V(6); PG8_BAR; PG8_MMA(1, 1, At, B1); PG8_BAR;
;       PG8_LDB(B0, 1, 0); PG8_SCHED; PG8_LDA(At, 1, 0); PG8_STAGE(PG8_SA(0, 1), a2 + hstep, voffA);
;       PG8_WAIT_L(8); PG8_BAR; PG8_WAIT_L(0); PG8_MMA(0, 0, At, B0); PG8_BAR; PG8_SCHED;
;       PG8_LDB(B1, 1, 1); PG8_STAGE(PG8_SB(1, 0), b3, voffB);
;       PG8_BAR; PG8_WAIT_L(0); PG8_MMA(0, 1, At, B1); PG8_BAR;
;       PG8_LDA(At, 1, 1); PG8_STAGE(PG8_SA(1, 0), a3, voffA);
	s_add_u32 s68, s68, s42
	s_addc_u32 s69, s69, s43
	s_add_i32 s1, s1, s74
	v_lshl_add_u64 v[216:217], s[68:69], 0, v[138:139]
	s_mov_b32 m0, s1
	v_lshl_add_u64 v[218:219], s[68:69], 0, v[152:153]
	global_load_lds_dwordx4 v[216:217], off
	s_add_i32 m0, s1, 0x2000
	s_nop 0
	global_load_lds_dwordx4 v[218:219], off
	s_waitcnt vmcnt(6)
	s_barrier
	s_setprio 1
	v_mfma_f32_16x16x32_bf16 v[28:31], v[248:251], v[166:169], v[28:31]
	v_mfma_f32_16x16x32_bf16 v[24:27], v[210:213], v[166:169], v[24:27]
	v_mfma_f32_16x16x32_bf16 v[20:23], v[248:251], v[174:177], v[20:23]
	v_mfma_f32_16x16x32_bf16 v[16:19], v[210:213], v[174:177], v[16:19]
	v_mfma_f32_16x16x32_bf16 v[12:15], v[248:251], v[182:185], v[12:15]
	v_mfma_f32_16x16x32_bf16 v[8:11], v[210:213], v[182:185], v[8:11]
	v_mfma_f32_16x16x32_bf16 v[4:7], v[248:251], v[190:193], v[4:7]
	v_mfma_f32_16x16x32_bf16 v[0:3], v[210:213], v[190:193], v[0:3]
	v_mfma_f32_16x16x32_bf16 v[28:31], v[198:201], v[170:173], v[28:31]
	v_mfma_f32_16x16x32_bf16 v[24:27], v[194:197], v[170:173], v[24:27]
	v_mfma_f32_16x16x32_bf16 v[20:23], v[198:201], v[178:181], v[20:23]
	v_mfma_f32_16x16x32_bf16 v[16:19], v[194:197], v[178:181], v[16:19]
	v_mfma_f32_16x16x32_bf16 v[12:15], v[198:201], v[186:189], v[12:15]
	v_mfma_f32_16x16x32_bf16 v[8:11], v[194:197], v[186:189], v[8:11]
	v_mfma_f32_16x16x32_bf16 v[4:7], v[198:201], v[244:247], v[4:7]
	v_mfma_f32_16x16x32_bf16 v[0:3], v[194:197], v[244:247], v[0:3]
	s_setprio 0
	s_add_i32 s1, 0, 0x18000
	v_add_u32_e32 v140, s1, v205
	s_barrier
	ds_read_b128 v[128:131], v140
	ds_read_b128 v[132:135], v140 offset:1024
	ds_read_b128 v[158:161], v140 offset:2048
	ds_read_b128 v[162:165], v140 offset:3072
	s_add_u32 s10, s10, s42
	s_addc_u32 s11, s11, s43
	s_mov_b32 m0, s83
	v_lshl_add_u64 v[198:199], s[10:11], 0, v[148:149]
	ds_read_b128 v[166:169], v208 offset:32768
	ds_read_b128 v[170:173], v208 offset:33792
	ds_read_b128 v[174:177], v208 offset:34816
	ds_read_b128 v[178:181], v208 offset:35840
	ds_read_b128 v[182:185], v208 offset:36864
	ds_read_b128 v[186:189], v208 offset:37888
	ds_read_b128 v[190:193], v208 offset:38912
	ds_read_b128 v[194:197], v208 offset:39936
	global_load_lds_dwordx4 v[198:199], off
	v_lshl_add_u64 v[198:199], s[10:11], 0, v[150:151]
	s_mov_b32 m0, s84
	s_nop 0
	global_load_lds_dwordx4 v[198:199], off
	s_waitcnt lgkmcnt(8)
	s_barrier
	s_waitcnt lgkmcnt(0)
	s_setprio 1
	s_waitcnt lgkmcnt(0)
	v_mfma_f32_16x16x32_bf16 v[124:127], v[128:131], v[166:169], v[124:127]
	v_mfma_f32_16x16x32_bf16 v[120:123], v[158:161], v[166:169], v[120:123]
	v_mfma_f32_16x16x32_bf16 v[116:119], v[128:131], v[174:177], v[116:119]
	v_mfma_f32_16x16x32_bf16 v[112:115], v[158:161], v[174:177], v[112:115]
	v_mfma_f32_16x16x32_bf16 v[108:111], v[128:131], v[182:185], v[108:111]
	v_mfma_f32_16x16x32_bf16 v[104:107], v[158:161], v[182:185], v[104:107]
	v_mfma_f32_16x16x32_bf16 v[100:103], v[128:131], v[190:193], v[100:103]
	v_mfma_f32_16x16x32_bf16 v[96:99], v[158:161], v[190:193], v[96:99]
	v_mfma_f32_16x16x32_bf16 v[124:127], v[132:135], v[170:173], v[124:127]
	v_mfma_f32_16x16x32_bf16 v[120:123], v[162:165], v[170:173], v[120:123]
	v_mfma_f32_16x16x32_bf16 v[116:119], v[132:135], v[178:181], v[116:119]
	v_mfma_f32_16x16x32_bf16 v[112:115], v[162:165], v[178:181], v[112:115]
	v_mfma_f32_16x16x32_bf16 v[108:111], v[132:135], v[186:189], v[108:111]
	v_mfma_f32_16x16x32_bf16 v[104:107], v[162:165], v[186:189], v[104:107]
	v_mfma_f32_16x16x32_bf16 v[100:103], v[132:135], v[194:197], v[100:103]
	v_mfma_f32_16x16x32_bf16 v[96:99], v[162:165], v[194:197], v[96:99]
	s_setprio 0
	s_barrier
	s_add_i32 s10, 0, 0x1c000
	s_add_i32 s1, s1, s74
	v_add_u32_e32 v140, s10, v205
	v_lshl_add_u64 v[136:137], v[136:137], 0, s[2:3]
	s_mov_b32 m0, s1
	ds_read_b128 v[198:201], v140
	ds_read_b128 v[210:213], v140 offset:1024
	ds_read_b128 v[244:247], v140 offset:2048
	ds_read_b128 v[248:251], v140 offset:3072
	global_load_lds_dwordx4 v[136:137], off
	v_lshl_add_u64 v[136:137], v[220:221], 0, s[2:3]
	s_add_i32 m0, s1, 0x2000
	s_nop 0
	global_load_lds_dwordx4 v[136:137], off
	s_barrier
; #define PG8_STAGE(bufoff, gbase, voff) do { _Pragma("unroll") for (int _i = 0; _i < 2; ++_i) \
;     __builtin_amdgcn_global_load_lds((const unsigned*)((const char*)(gbase) + (voff)[_i]), (LAS unsigned*)(lds + (bufoff) + ldsw + _i * 8192), 16, 0, 0); } while (0)
; #define PG8_LDA(dst, b, h) do { _Pragma("unroll") for (int m = 0; m < 4; ++m) _Pragma("unroll") for (int k = 0; k < 2; ++k) dst[m][k] = *(const LAS bf16x8*)(lds + PG8_SA(b, h) + aoff + m * 2048 + k * 1024); } while (0)
; #define PG8_MMA(ai, bj, At, Bt) do { __builtin_amdgcn_s_setprio(1); _Pragma("unroll") for (int m = 0; m < 4; ++m) _Pragma("unroll") for (int n = 0; n < 2; ++n) _Pragma("unroll") for (int k = 0; k < 2; ++k) \
;     acc[ai][bj][m][n] = __builtin_amdgcn_mfma_f32_16x16x32_bf16(Bt[n][k], At[m][k], acc[ai][bj][m][n], 0, 0, 0); __builtin_amdgcn_s_setprio(0); } while (0)
; #define PG8_WAIT_V(n) asm volatile("s_waitcnt vmcnt(" #n ")" ::: "memory")
; #define PG8_WAIT_L(n) asm volatile("s_waitcnt lgkmcnt(" #n ")" ::: "memory")
; #define PG8_BAR __builtin_amdgcn_s_barrier()
; #define PG8_SCHED __builtin_amdgcn_sched_barrier(0)
; __device__ __forceinline__ void gemm_phase(LAS unsigned char* lds, const Gemm g, const StaticOrder& S, const Epi& E, const int tid) {
;     ...
;       PG8_LDA(At, 1, 1); PG8_STAGE(PG8_SA(1, 0), a3, voffA);
;       PG8_BAR; PG8_WAIT_L(0); PG8_MMA(1, 0, At, B0); PG8_BAR; PG8_SCHED;
;       PG8_STAGE(PG8_SB(1, 1), b3 + hstep, voffB);
;       PG8_WAIT_V(6); PG8_BAR; PG8_MMA(1, 1, At, B1); PG8_BAR;
	s_waitcnt lgkmcnt(0)
	s_setprio 1
	s_waitcnt lgkmcnt(0)
	v_mfma_f32_16x16x32_bf16 v[60:63], v[198:201], v[166:169], v[60:63]
	v_mfma_f32_16x16x32_bf16 v[56:59], v[244:247], v[166:169], v[56:59]
	v_mfma_f32_16x16x32_bf16 v[52:55], v[198:201], v[174:177], v[52:55]
	v_mfma_f32_16x16x32_bf16 v[48:51], v[244:247], v[174:177], v[48:51]
	v_mfma_f32_16x16x32_bf16 v[44:47], v[198:201], v[182:185], v[44:47]
	v_mfma_f32_16x16x32_bf16 v[40:43], v[244:247], v[182:185], v[40:43]
	v_mfma_f32_16x16x32_bf16 v[36:39], v[198:201], v[190:193], v[36:39]
	v_mfma_f32_16x16x32_bf16 v[32:35], v[244:247], v[190:193], v[32:35]
	v_mfma_f32_16x16x32_bf16 v[60:63], v[210:213], v[170:173], v[60:63]
	v_mfma_f32_16x16x32_bf16 v[56:59], v[248:251], v[170:173], v[56:59]
	v_mfma_f32_16x16x32_bf16 v[52:55], v[210:213], v[178:181], v[52:55]
	v_mfma_f32_16x16x32_bf16 v[48:51], v[248:251], v[178:181], v[48:51]
	v_mfma_f32_16x16x32_bf16 v[44:47], v[210:213], v[186:189], v[44:47]
	v_mfma_f32_16x16x32_bf16 v[40:43], v[248:251], v[186:189], v[40:43]
	v_mfma_f32_16x16x32_bf16 v[36:39], v[210:213], v[194:197], v[36:39]
	v_mfma_f32_16x16x32_bf16 v[32:35], v[248:251], v[194:197], v[32:35]
	s_setprio 0
	s_mov_b32 m0, s86
	v_lshl_add_u64 v[136:137], v[214:215], 0, s[2:3]
	s_barrier
	ds_read_b128 v[166:169], v208 offset:49152
	ds_read_b128 v[170:173], v208 offset:50176
	ds_read_b128 v[174:177], v208 offset:51200
	ds_read_b128 v[178:181], v208 offset:52224
	ds_read_b128 v[182:185], v208 offset:53248
	ds_read_b128 v[186:189], v208 offset:54272
	ds_read_b128 v[190:193], v208 offset:55296
	ds_read_b128 v[194:197], v208 offset:56320
	global_load_lds_dwordx4 v[136:137], off
	v_lshl_add_u64 v[136:137], v[202:203], 0, s[2:3]
	s_mov_b32 m0, s87
	s_nop 0
	global_load_lds_dwordx4 v[136:137], off
	s_barrier
	s_waitcnt lgkmcnt(0)
	s_setprio 1
	s_waitcnt lgkmcnt(0)
	v_mfma_f32_16x16x32_bf16 v[92:95], v[128:131], v[166:169], v[92:95]
	v_mfma_f32_16x16x32_bf16 v[88:91], v[158:161], v[166:169], v[88:91]
	v_mfma_f32_16x16x32_bf16 v[84:87], v[128:131], v[174:177], v[84:87]
	v_mfma_f32_16x16x32_bf16 v[80:83], v[158:161], v[174:177], v[80:83]
	v_mfma_f32_16x16x32_bf16 v[76:79], v[128:131], v[182:185], v[76:79]
	v_mfma_f32_16x16x32_bf16 v[72:75], v[158:161], v[182:185], v[72:75]
	v_mfma_f32_16x16x32_bf16 v[68:71], v[128:131], v[190:193], v[68:71]
	v_mfma_f32_16x16x32_bf16 v[64:67], v[158:161], v[190:193], v[64:67]
	v_mfma_f32_16x16x32_bf16 v[92:95], v[132:135], v[170:173], v[92:95]
	v_mfma_f32_16x16x32_bf16 v[88:91], v[162:165], v[170:173], v[88:91]
	v_mfma_f32_16x16x32_bf16 v[84:87], v[132:135], v[178:181], v[84:87]
	v_mfma_f32_16x16x32_bf16 v[80:83], v[162:165], v[178:181], v[80:83]
	v_mfma_f32_16x16x32_bf16 v[76:79], v[132:135], v[186:189], v[76:79]
	v_mfma_f32_16x16x32_bf16 v[72:75], v[162:165], v[186:189], v[72:75]
	v_mfma_f32_16x16x32_bf16 v[68:71], v[132:135], v[194:197], v[68:71]
	v_mfma_f32_16x16x32_bf16 v[64:67], v[162:165], v[194:197], v[64:67]
	s_setprio 0
	s_barrier
	s_add_i32 s1, s10, s74
	v_lshl_add_u64 v[128:129], v[216:217], 0, s[2:3]
	s_mov_b32 m0, s1
	s_nop 0
	global_load_lds_dwordx4 v[128:129], off
	v_lshl_add_u64 v[128:129], v[218:219], 0, s[2:3]
	s_add_i32 m0, s1, 0x2000
	s_nop 0
	global_load_lds_dwordx4 v[128:129], off
	s_waitcnt vmcnt(6)
	s_barrier
	s_setprio 1
	v_mfma_f32_16x16x32_bf16 v[28:31], v[198:201], v[166:169], v[28:31]
	v_mfma_f32_16x16x32_bf16 v[24:27], v[244:247], v[166:169], v[24:27]
	v_mfma_f32_16x16x32_bf16 v[20:23], v[198:201], v[174:177], v[20:23]
	v_mfma_f32_16x16x32_bf16 v[16:19], v[244:247], v[174:177], v[16:19]
	v_mfma_f32_16x16x32_bf16 v[12:15], v[198:201], v[182:185], v[12:15]
	v_mfma_f32_16x16x32_bf16 v[8:11], v[244:247], v[182:185], v[8:11]
	v_mfma_f32_16x16x32_bf16 v[4:7], v[198:201], v[190:193], v[4:7]
	v_mfma_f32_16x16x32_bf16 v[0:3], v[244:247], v[190:193], v[0:3]
	v_mfma_f32_16x16x32_bf16 v[28:31], v[210:213], v[170:173], v[28:31]
	v_mfma_f32_16x16x32_bf16 v[24:27], v[248:251], v[170:173], v[24:27]
	v_mfma_f32_16x16x32_bf16 v[20:23], v[210:213], v[178:181], v[20:23]
	v_mfma_f32_16x16x32_bf16 v[16:19], v[248:251], v[178:181], v[16:19]
	v_mfma_f32_16x16x32_bf16 v[12:15], v[210:213], v[186:189], v[12:15]
	v_mfma_f32_16x16x32_bf16 v[8:11], v[248:251], v[186:189], v[8:11]
	v_mfma_f32_16x16x32_bf16 v[4:7], v[210:213], v[194:197], v[4:7]
	v_mfma_f32_16x16x32_bf16 v[0:3], v[248:251], v[194:197], v[0:3]
	s_setprio 0
	s_add_u32 vcc_lo, vcc_lo, 0x100
	s_addc_u32 vcc_hi, vcc_hi, 0
	s_add_u32 s8, s8, 0x100
	s_addc_u32 s9, s9, 0
	s_cmp_ge_i32 s70, s23
	s_mov_b32 s10, s70
	s_barrier
	s_cbranch_scc0 .LBB0_299
